# speedup vs baseline: 1.0061x; 1.0061x over previous
; DEVI void tconv(const float* __restrict__ W, u16* __restrict__ Wt, int K, int N, float* lds) {
;   const int ntile = (K / 64) * (N / 128);
;   TcPre R;
;   int t = blockIdx.x;
;   if (t < ntile) tconv_load(W, N, t, R);
;   for (; t < ntile; t += gridDim.x) {
;     TcPre C = R;
;     int nx = t + (int)gridDim.x;
;     tconv_load(W, N, nx < ntile ? nx : t, R);
;     tconv_store(C, Wt, K, N, t, lds, false);
;   }
; }
; __device__ NOINL void phase0(const Params& p, char* smem) {
;     ...
;   float* lds = (float*)smem;
;   tconv(p.w_in, (u16*)(ws + O_WIN), 4096, NIN, lds);
;   tconv(p.w_mem, (u16*)(ws + O_WMEM), 4096, 2048, lds);
.LBB0_102:
	s_or_b64 exec, exec, s[4:5]
	s_mov_b32 s81, 2
	s_movk_i32 s82, 0x1e00
	s_branch .Ldcv0_entry

; DEVI void lds_barrier() { asm volatile("s_waitcnt lgkmcnt(0)" ::: "memory"); __builtin_amdgcn_s_barrier(); asm volatile("" ::: "memory"); }
; DEVI void deferred_conv(const Params& p, char* smem, const int which) {
;   float* lds = (float*)smem;
;   int* qs = (int*)(smem + 40960);
;   unsigned* ctr = (unsigned*)(p.ws + O_CTR) + which * 16;
;   const int tlo = which ? DQ_WO + DQ_WUP : 0, thi = which ? DQ_TOTAL : DQ_WO + DQ_WUP;
;   char* ws = p.ws;
;   for (;;) {
;     if (threadIdx.x == 0) *qs = tlo + (int)atomicAdd(ctr, (unsigned)DQ_GRAB);
;     lds_barrier();
;     int base = *qs;
;     lds_barrier();
;     if (base >= thi) break;
;     TcPre R[DQ_GRAB];
; #pragma unroll
;     for (int u = 0; u < DQ_GRAB; ++u) {
;       int t = base + u;
;       if (t < thi) {
;         if (t < DQ_WO) tconv_load(p.w_o, 4096, t, R[u]);
;         else if (t < DQ_WO + DQ_WUP) tconv_load(p.w_up, NUP, t - DQ_WO, R[u]);
;         else tconv_load(p.w_down, 4096, t - DQ_WO - DQ_WUP, R[u]);
;       }
;     }
.LBB0_183:
	s_mov_b32 s81, 0
	s_movk_i32 s82, 0x3300
.Ldcv0_entry:
	s_waitcnt lgkmcnt(0)
	s_barrier
	v_mov_b32_e32 v50, 0
	v_mov_b32_e32 v51, 4
	v_mov_b32_e32 v84, 0x10400
	v_lshrrev_b32_e32 v55, 5, v164
	v_and_b32_e32 v56, 31, v164
	v_lshlrev_b32_e32 v56, 4, v56
	v_lshrrev_b32_e32 v53, 3, v164
	v_and_b32_e32 v57, 7, v164
	v_lshlrev_b32_e32 v57, 4, v57
	s_mov_b32 s6, 0x2000
	v_mad_u32_u24 v57, v53, s6, v57
	s_movk_i32 s6, 0x204
	v_mad_u32_u24 v58, v55, s6, v56
	v_add_u32_e32 v59, 0x2040, v58
	v_add_u32_e32 v60, 0x4080, v58
	v_add_u32_e32 v61, 0x60c0, v58
	v_add_u32_e32 v62, 0x8100, v58
	v_add_u32_e32 v63, 0xa140, v58
	v_add_u32_e32 v64, 0xc180, v58
	v_add_u32_e32 v65, 0xe1c0, v58
	v_and_b32_e32 v66, 7, v164
	s_movk_i32 s6, 0x1020
	v_lshlrev_b32_e32 v53, 2, v53
	v_mad_u32_u24 v66, v66, s6, v53
	v_add_u32_e32 v67, 0x408, v66
	v_add_u32_e32 v68, 0x810, v66
	v_add_u32_e32 v69, 0xc18, v66
	v_add_u32_e32 v70, 0x100, v66
	v_add_u32_e32 v71, 0x508, v66
	v_add_u32_e32 v72, 0x910, v66
	v_add_u32_e32 v73, 0xd18, v66
	v_add_u32_e32 v74, 0x8100, v66
	v_add_u32_e32 v75, 0x8508, v66
	v_add_u32_e32 v76, 0x8910, v66
	v_add_u32_e32 v77, 0x8d18, v66
	v_add_u32_e32 v78, 0x8200, v66
	v_add_u32_e32 v79, 0x8608, v66
	v_add_u32_e32 v80, 0x8a10, v66
	v_add_u32_e32 v81, 0x8e18, v66
	s_add_u32 s10, s56, 0x2b403000
	s_addc_u32 s11, s57, 0
	s_cmp_eq_u32 s81, 2
	s_cbranch_scc0 .Ldcv0_ctr_ok
	s_add_u32 s10, s10, 0x80
	s_addc_u32 s11, s11, 0
.Ldcv0_ctr_ok:
	v_readfirstlane_b32 s33, v164
	s_mov_b64 s[76:77], exec
	s_cmp_lg_u32 s33, 0
	s_cbranch_scc1 .Ldcv0_q0
	s_mov_b64 exec, 1
	global_atomic_add v82, v50, v51, s[10:11] sc0
	global_atomic_add v83, v50, v51, s[10:11] sc0
	s_waitcnt vmcnt(0)
	ds_write_b64 v84, v[82:83]
	s_mov_b64 exec, s[76:77]
.Ldcv0_q0:
	s_waitcnt lgkmcnt(0)
	s_barrier
	ds_read_b64 v[82:83], v84
	s_waitcnt lgkmcnt(0)
	v_readfirstlane_b32 s3, v82
	v_readfirstlane_b32 s4, v83
	s_cmp_ge_u32 s3, s82
	s_cbranch_scc1 .Ldcv0_done
	s_cmp_eq_u32 s81, 2
	s_cbranch_scc0 .Ldcv0_so_pro
	s_cmp_lt_u32 s3, 0x1a00
	s_cbranch_scc0 .Ldcv0_sm_pro
	s_lshr_b32 s7, s3, 3
	s_mul_i32 s6, s7, 0x4ec5
	s_lshr_b32 s6, s6, 18
	s_mul_i32 s15, s6, 0x68
	s_sub_u32 s7, s3, s15
	s_mul_i32 s6, s6, 0x340000
	s_lshl_b32 s7, s7, 9
	s_add_u32 s6, s6, s7
	s_add_u32 s68, s42, s6
	s_addc_u32 s69, s43, 0
	s_mov_b32 s70, 0xd0000
	s_mov_b32 s88, 0xd000
	s_branch .Ldcv0_sdn_pro
.Ldcv0_sm_pro:
	s_sub_u32 s7, s3, 0x1a00
	s_lshr_b32 s6, s7, 4
	s_and_b32 s7, s7, 15
	s_lshl_b32 s6, s6, 19
	s_lshl_b32 s7, s7, 9
	s_add_u32 s6, s6, s7
	s_add_u32 s68, s44, s6
	s_addc_u32 s69, s45, 0
	s_mov_b32 s70, 0x20000
	s_movk_i32 s88, 0x2000
	s_branch .Ldcv0_sdn_pro
.Ldcv0_so_pro:
	s_cmp_lt_u32 s3, 0x800
	s_cbranch_scc0 .Ldcv0_sup_pro
	s_lshr_b32 s6, s3, 5
	s_and_b32 s7, s3, 31
	s_lshl_b32 s6, s6, 20
	s_lshl_b32 s7, s7, 9
	s_add_u32 s6, s6, s7
	s_add_u32 s68, s46, s6
	s_addc_u32 s69, s47, 0
	s_mov_b32 s70, 0x40000
	s_movk_i32 s88, 0x4000
	s_branch .Ldcv0_sdn_pro

; DEVI void lds_barrier() { asm volatile("s_waitcnt lgkmcnt(0)" ::: "memory"); __builtin_amdgcn_s_barrier(); asm volatile("" ::: "memory"); }
; DEVI void deferred_conv(const Params& p, char* smem, const int which) {
;     ...
;   for (;;) {
;     if (threadIdx.x == 0) *qs = tlo + (int)atomicAdd(ctr, (unsigned)DQ_GRAB);
;     lds_barrier();
;     int base = *qs;
;     lds_barrier();
;     if (base >= thi) break;
;     TcPre R[DQ_GRAB];
; #pragma unroll
;     for (int u = 0; u < DQ_GRAB; ++u) {
;       int t = base + u;
;       if (t < thi) {
;         if (t < DQ_WO) tconv_load(p.w_o, 4096, t, R[u]);
;         else if (t < DQ_WO + DQ_WUP) tconv_load(p.w_up, NUP, t - DQ_WO, R[u]);
;         else tconv_load(p.w_down, 4096, t - DQ_WO - DQ_WUP, R[u]);
;       }
;     }
; #pragma unroll
;     for (int u = 0; u < DQ_GRAB; ++u) {
;       int t = base + u;
;       if (t < thi) {
;         if (t < DQ_WO) tconv_store(R[u], (u16*)(ws + O_WO), 4096, 4096, t, lds, false);
;         else if (t < DQ_WO + DQ_WUP) tconv_store(R[u], (u16*)(ws + O_WUP), 4096, NUP, t - DQ_WO, lds, true);
;         else tconv_store(R[u], (u16*)(ws + O_WDN), DFF, 4096, t - DQ_WO - DQ_WUP, lds, false);
;       }
;     }
.Ldcv0_loop:
	s_cmp_ge_u32 s4, s82
	s_cbranch_scc1 .Ldcv0_last
	s_cmp_eq_u32 s81, 2
	s_cbranch_scc0 .Ldcv0_do_st
	s_cmp_lt_u32 s3, 0x1a00
	s_cbranch_scc0 .Ldcv0_dm_st
	s_lshr_b32 s7, s3, 3
	s_mul_i32 s6, s7, 0x4ec5
	s_lshr_b32 s6, s6, 18
	s_mul_i32 s15, s6, 0x68
	s_sub_u32 s86, s3, s15
	s_lshl_b32 s6, s6, 7
	s_add_u32 s6, s6, 0x4000000
	s_mov_b32 s87, 0
	s_branch .Ldcv0_ddn_st
.Ldcv0_dm_st:
	s_sub_u32 s7, s3, 0x1a00
	s_lshr_b32 s6, s7, 4
	s_and_b32 s86, s7, 15
	s_lshl_b32 s6, s6, 7
	s_add_u32 s6, s6, 0x1ca00000
	s_mov_b32 s87, 0
	s_branch .Ldcv0_ddn_st

; DEVI void deferred_conv(const Params& p, char* smem, const int which) {
;     ...
;     for (int u = 0; u < DQ_GRAB; ++u) {
;       int t = base + u;
;       if (t < thi) {
;         if (t < DQ_WO) tconv_load(p.w_o, 4096, t, R[u]);
;         else if (t < DQ_WO + DQ_WUP) tconv_load(p.w_up, NUP, t - DQ_WO, R[u]);
;         else tconv_load(p.w_down, 4096, t - DQ_WO - DQ_WUP, R[u]);
;       }
;     }
; #pragma unroll
;     for (int u = 0; u < DQ_GRAB; ++u) {
;       int t = base + u;
;       if (t < thi) {
;         if (t < DQ_WO) tconv_store(R[u], (u16*)(ws + O_WO), 4096, 4096, t, lds, false);
;         else if (t < DQ_WO + DQ_WUP) tconv_store(R[u], (u16*)(ws + O_WUP), 4096, NUP, t - DQ_WO, lds, true);
;         else tconv_store(R[u], (u16*)(ws + O_WDN), DFF, 4096, t - DQ_WO - DQ_WUP, lds, false);
;       }
.Ldcv0_ddn_st:
	s_add_u32 s84, s56, s6
	s_addc_u32 s85, s57, 0
	s_cmp_eq_u32 s81, 2
	s_cbranch_scc0 .Ldcv0_so_st
	s_cmp_lt_u32 s4, 0x1a00
	s_cbranch_scc0 .Ldcv0_sm_st
	s_lshr_b32 s7, s4, 3
	s_mul_i32 s6, s7, 0x4ec5
	s_lshr_b32 s6, s6, 18
	s_mul_i32 s15, s6, 0x68
	s_sub_u32 s7, s4, s15
	s_mul_i32 s6, s6, 0x340000
	s_lshl_b32 s7, s7, 9
	s_add_u32 s6, s6, s7
	s_add_u32 s68, s42, s6
	s_addc_u32 s69, s43, 0
	s_mov_b32 s70, 0xd0000
	s_mov_b32 s88, 0xd000
	s_branch .Ldcv0_sdn_st
.Ldcv0_sm_st:
	s_sub_u32 s7, s4, 0x1a00
	s_lshr_b32 s6, s7, 4
	s_and_b32 s7, s7, 15
	s_lshl_b32 s6, s6, 19
	s_lshl_b32 s7, s7, 9
	s_add_u32 s6, s6, s7
	s_add_u32 s68, s44, s6
	s_addc_u32 s69, s45, 0
	s_mov_b32 s70, 0x20000
	s_movk_i32 s88, 0x2000
	s_branch .Ldcv0_sdn_st
.Ldcv0_so_st:
	s_cmp_lt_u32 s4, 0x800
	s_cbranch_scc0 .Ldcv0_sup_st
	s_lshr_b32 s6, s4, 5
	s_and_b32 s7, s4, 31
	s_lshl_b32 s6, s6, 20
	s_lshl_b32 s7, s7, 9
	s_add_u32 s6, s6, s7
	s_add_u32 s68, s46, s6
	s_addc_u32 s69, s47, 0
	s_mov_b32 s70, 0x40000
	s_movk_i32 s88, 0x4000
	s_branch .Ldcv0_sdn_st

; DEVI void deferred_conv(const Params& p, char* smem, const int which) {
;     ...
;     for (int u = 0; u < DQ_GRAB; ++u) {
;       int t = base + u;
;       if (t < thi) {
;         if (t < DQ_WO) tconv_store(R[u], (u16*)(ws + O_WO), 4096, 4096, t, lds, false);
;         else if (t < DQ_WO + DQ_WUP) tconv_store(R[u], (u16*)(ws + O_WUP), 4096, NUP, t - DQ_WO, lds, true);
;         else tconv_store(R[u], (u16*)(ws + O_WDN), DFF, 4096, t - DQ_WO - DQ_WUP, lds, false);
;       }
;     }
.Ldcv0_last:
	s_cmp_eq_u32 s81, 2
	s_cbranch_scc0 .Ldcv0_do_la
	s_cmp_lt_u32 s3, 0x1a00
	s_cbranch_scc0 .Ldcv0_dm_la
	s_lshr_b32 s7, s3, 3
	s_mul_i32 s6, s7, 0x4ec5
	s_lshr_b32 s6, s6, 18
	s_mul_i32 s15, s6, 0x68
	s_sub_u32 s86, s3, s15
	s_lshl_b32 s6, s6, 7
	s_add_u32 s6, s6, 0x4000000
	s_mov_b32 s87, 0
	s_branch .Ldcv0_ddn_la

; DEVI void lds_barrier() { asm volatile("s_waitcnt lgkmcnt(0)" ::: "memory"); __builtin_amdgcn_s_barrier(); asm volatile("" ::: "memory"); }
; DEVI void deferred_conv(const Params& p, char* smem, const int which) {
;     ...
;   for (;;) {
;     if (threadIdx.x == 0) *qs = tlo + (int)atomicAdd(ctr, (unsigned)DQ_GRAB);
;     lds_barrier();
;     int base = *qs;
;     lds_barrier();
;     if (base >= thi) break;
; __device__ NOINL void phase0(const Params& p, char* smem) {
;     ...
;   tconv(p.w_mem, (u16*)(ws + O_WMEM), 4096, 2048, lds);
; }
.Ldcv0_done:
	s_waitcnt lgkmcnt(0)
	s_barrier
	s_cmp_eq_u32 s81, 2
	s_cbranch_scc1 .LBB0_108
